# window conversion limited to 3072 items per layer (3 per idle wave)
# baseline (speedup 1.0000x reference)
.LBB0_10:
	s_movk_i32 s0, 0x1a80
	v_writelane_b32 v247, s0, 0
	s_movk_i32 s0, 0xc00
	s_nop 0
	v_writelane_b32 v247, s0, 8
	s_movk_i32 s0, 0x1400
	s_nop 0
	v_writelane_b32 v247, s0, 9
	s_mov_b32 s0, 0
	s_nop 1
	v_writelane_b32 v247, s0, 1
	s_nop 1
	v_writelane_b32 v247, s0, 3
	s_nop 1
	v_writelane_b32 v247, s0, 6
	s_movk_i32 s0, 0xb00
	s_nop 0
	v_writelane_b32 v247, s0, 2
	s_movk_i32 s0, 0x3500
	s_nop 0
	v_writelane_b32 v247, s0, 5
	s_waitcnt lgkmcnt(0)
	s_lshl_b32 s0, s66, 3
	s_nop 0
	v_writelane_b32 v247, s0, 4
	s_lshr_b32 s100, s2, 6
	s_lshl_b32 s0, s74, 3
	s_add_i32 s100, s100, s0

.Lwin_all:
	v_writelane_b32 v242, s0, 0
	s_nop 1
	v_writelane_b32 v242, s1, 1
	s_nop 1
	v_writelane_b32 v242, s2, 2
	s_nop 1
	v_writelane_b32 v242, s3, 3
	s_nop 1
	v_writelane_b32 v242, s4, 4
	s_nop 1
	v_writelane_b32 v242, s5, 5
	s_nop 1
	v_writelane_b32 v242, s6, 6
	s_nop 1
	v_writelane_b32 v242, s7, 7
	s_nop 1
	v_writelane_b32 v242, s8, 8
	s_nop 1
	v_writelane_b32 v242, s9, 9
	s_nop 1
	v_writelane_b32 v242, s10, 10
	s_nop 1
	v_writelane_b32 v242, s11, 11
	s_nop 1
	v_writelane_b32 v242, s12, 12
	s_nop 1
	v_writelane_b32 v242, s13, 13
	s_nop 1
	v_writelane_b32 v242, s14, 14
	s_nop 1
	v_writelane_b32 v242, s15, 15
	s_nop 1
	v_writelane_b32 v242, s16, 16
	s_nop 1
	v_writelane_b32 v242, s17, 17
	s_nop 1
	v_writelane_b32 v242, s18, 18
	s_nop 1
	v_writelane_b32 v242, s19, 19
	s_nop 1
	v_writelane_b32 v242, s20, 20
	s_nop 1
	v_writelane_b32 v242, s21, 21
	s_nop 1
	v_writelane_b32 v242, s22, 22
	s_nop 1
	v_writelane_b32 v242, s23, 23
	s_nop 1
	v_writelane_b32 v242, s24, 24
	s_nop 1
	v_writelane_b32 v242, s25, 25
	s_nop 1
	v_writelane_b32 v242, s26, 26
	s_nop 1
	v_writelane_b32 v242, s27, 27
	s_nop 1
	v_writelane_b32 v242, s28, 28
	s_nop 1
	v_writelane_b32 v242, s29, 29
	s_nop 1
	v_writelane_b32 v242, s30, 30
	s_nop 1
	v_writelane_b32 v242, s31, 31
	s_nop 1
	v_writelane_b32 v242, s32, 32
	s_nop 1
	v_writelane_b32 v242, s33, 33
	s_nop 1
	v_writelane_b32 v242, s34, 34
	s_nop 1
	v_writelane_b32 v242, s35, 35
	s_nop 1
	v_writelane_b32 v242, s36, 36
	s_nop 1
	v_writelane_b32 v242, s37, 37
	s_nop 1
	v_writelane_b32 v242, s38, 38
	s_nop 1
	v_writelane_b32 v242, s39, 39
	s_nop 1
	v_writelane_b32 v242, s40, 40
	s_nop 1
	v_writelane_b32 v242, s41, 41
	s_nop 1
	v_writelane_b32 v242, s42, 42
	s_nop 1
	v_writelane_b32 v242, s43, 43
	s_nop 1
	v_writelane_b32 v242, s44, 44
	s_nop 1
	v_writelane_b32 v242, s45, 45
	s_nop 1
	v_writelane_b32 v242, s46, 46
	s_nop 1
	v_writelane_b32 v242, s47, 47
	s_nop 1
	v_writelane_b32 v242, s48, 48
	s_nop 1
	v_writelane_b32 v242, s49, 49
	s_nop 1
	v_writelane_b32 v242, s50, 50
	s_nop 1
	v_writelane_b32 v242, s51, 51
	s_nop 1
	v_writelane_b32 v242, s52, 52
	s_nop 1
	v_writelane_b32 v242, s53, 53
	s_nop 1
	v_writelane_b32 v242, s54, 54
	s_nop 1
	v_writelane_b32 v242, s55, 55
	s_nop 1
	v_writelane_b32 v242, s56, 56
	s_nop 1
	v_writelane_b32 v242, s57, 57
	s_nop 1
	v_writelane_b32 v242, s58, 58
	s_nop 1
	v_writelane_b32 v242, s59, 59
	s_nop 1
	v_writelane_b32 v242, s60, 60
	s_nop 1
	v_writelane_b32 v242, s61, 61
	s_nop 1
	v_writelane_b32 v242, s62, 62
	s_nop 1
	v_writelane_b32 v242, s63, 63
	s_nop 1
	v_writelane_b32 v243, s64, 0
	s_nop 1
	v_writelane_b32 v243, s65, 1
	s_nop 1
	v_writelane_b32 v243, s66, 2
	s_nop 1
	v_writelane_b32 v243, s67, 3
	s_nop 1
	v_writelane_b32 v243, s68, 4
	s_nop 1
	v_writelane_b32 v243, s69, 5
	s_nop 1
	v_writelane_b32 v243, s70, 6
	s_nop 1
	v_writelane_b32 v243, s71, 7
	s_nop 1
	v_writelane_b32 v243, s72, 8
	s_nop 1
	v_writelane_b32 v243, s73, 9
	s_nop 1
	v_writelane_b32 v243, s74, 10
	s_nop 1
	v_writelane_b32 v243, s75, 11
	s_nop 1
	v_writelane_b32 v243, s76, 12
	s_nop 1
	v_writelane_b32 v243, s77, 13
	s_nop 1
	v_writelane_b32 v243, s78, 14
	s_nop 1
	v_writelane_b32 v243, s79, 15
	s_nop 1
	v_writelane_b32 v243, s80, 16
	s_nop 1
	v_writelane_b32 v243, s81, 17
	s_nop 1
	v_writelane_b32 v243, s82, 18
	s_nop 1
	v_writelane_b32 v243, s83, 19
	s_nop 1
	v_writelane_b32 v243, s84, 20
	s_nop 1
	v_writelane_b32 v243, s85, 21
	s_nop 1
	v_writelane_b32 v243, s86, 22
	s_nop 1
	v_writelane_b32 v243, s87, 23
	s_nop 1
	v_writelane_b32 v243, s88, 24
	s_nop 1
	v_writelane_b32 v243, s89, 25
	s_nop 1
	v_writelane_b32 v243, s90, 26
	s_nop 1
	v_writelane_b32 v243, s91, 27
	s_nop 1
	v_writelane_b32 v243, s92, 28
	s_nop 1
	v_writelane_b32 v243, s93, 29
	s_nop 1
	v_writelane_b32 v243, s94, 30
	s_nop 1
	v_writelane_b32 v243, s95, 31
	s_nop 1
	v_writelane_b32 v243, s96, 32
	s_nop 1
	v_writelane_b32 v243, s97, 33
	s_nop 1
	v_writelane_b32 v243, s98, 34
	s_nop 1
	v_writelane_b32 v243, s99, 35
	s_nop 1
	v_writelane_b32 v243, vcc_lo, 36
	s_nop 1
	v_writelane_b32 v243, vcc_hi, 37
	s_mov_b64 s[0:1], exec
	s_nop 1
	v_writelane_b32 v243, s0, 38
	s_nop 1
	v_writelane_b32 v243, s1, 39
	s_mov_b64 exec, -1
	v_mov_b32_e32 v244, v241
	v_mov_b32_e32 v245, v4
	v_mov_b32_e32 v246, v33
	s_cmp_gt_u32 s70, 2
	s_cselect_b32 s4, 1, 0
	s_nop 0
	v_writelane_b32 v247, s4, 3
	s_movk_i32 s4, 0xc00
	s_nop 0
	v_writelane_b32 v247, s4, 0
	s_nop 1
	v_writelane_b32 v247, s4, 5
	s_movk_i32 s4, 0x7fff
	s_nop 0
	v_writelane_b32 v247, s4, 9
	s_nop 1
	v_writelane_b32 v247, s4, 8
	s_movk_i32 s4, 0xb00
	s_nop 0
	v_writelane_b32 v247, s4, 1
	s_movk_i32 s4, 0x1400
	s_nop 0
	v_writelane_b32 v247, s4, 2
	s_lshl_b32 s4, s66, 3
	s_cmpk_eq_i32 s66, 0x100
	s_cselect_b32 s4, 0x400, s4
	s_cselect_b32 s3, 0x400, 0
	s_nop 0
	v_writelane_b32 v247, s4, 4
	s_mov_b32 s4, 1
	s_nop 0
	v_writelane_b32 v247, s4, 6
	s_load_dwordx8 s[8:15], s[30:31], 0x0
	s_load_dwordx4 s[24:27], s[30:31], 0x20
	s_load_dwordx2 s[6:7], s[30:31], 0x30
	s_load_dwordx4 s[64:67], s[30:31], 0xb0
	v_readfirstlane_b32 s2, v156
	s_lshl_b32 s4, s74, 3
	s_lshr_b32 s100, s2, 6
	s_add_i32 s100, s100, s4
	s_sub_i32 s100, s100, s3
	s_waitcnt lgkmcnt(0)
	s_branch .Lconv_pre
